# layer-1 weight-conversion loop: the 24 remaining serialized gain loads (3 tiles x 8) issued per tile with one wait
# baseline (speedup 1.0000x reference)
.LBB0_1524:
	v_cndmask_b32_e64 v4, 0, 1, s[16:17]
	v_cmp_ne_u32_e64 s[6:7], 1, v4
	s_andn2_b64 vcc, exec, s[16:17]
	ds_write_b32 v6, v7 offset:14560
	s_cbranch_vccnz .LBB0_1543
	s_and_b64 vcc, exec, s[4:5]
	v_mul_f32_e32 v4, s30, v33
	s_cbranch_vccnz .LBB0_1527
	v_add_u32_e32 v30, s12, v2
	v_readlane_b32 s48, v250, 26
	v_ashrrev_i32_e32 v31, 31, v30
	v_readlane_b32 s49, v250, 27
	v_readlane_b32 s50, v250, 28
	v_readlane_b32 s51, v250, 29
	v_lshl_add_u64 v[30:31], v[30:31], 2, s[48:49]
	global_load_dword v108, v[30:31], off
	global_load_dword v109, v[30:31], off offset:32
	global_load_dword v110, v[30:31], off offset:64
	global_load_dword v111, v[30:31], off offset:96
	global_load_dword v112, v[30:31], off offset:128
	global_load_dword v113, v[30:31], off offset:160
	global_load_dword v114, v[30:31], off offset:192
	global_load_dword v115, v[30:31], off offset:224
	v_readlane_b32 s52, v250, 30
	v_readlane_b32 s53, v250, 31
	v_readlane_b32 s54, v250, 32
	v_readlane_b32 s55, v250, 33
	v_readlane_b32 s56, v250, 34
	v_readlane_b32 s57, v250, 35
	v_readlane_b32 s58, v250, 36
	v_readlane_b32 s59, v250, 37
	v_readlane_b32 s60, v250, 38
	v_readlane_b32 s61, v250, 39
	v_readlane_b32 s62, v250, 40
	v_readlane_b32 s63, v250, 41
	s_waitcnt vmcnt(0)
	v_mul_f32_e32 v4, v4, v108
.LBB0_1527:
	ds_write_b32 v6, v4 offset:16640
	s_and_b64 vcc, exec, s[4:5]
	v_mul_f32_e32 v4, s30, v3
	s_cbranch_vccnz .LBB0_1529
	s_ashr_i32 s13, s12, 31
	v_ashrrev_i32_e32 v3, 31, v2
	v_readlane_b32 s48, v250, 26
	v_lshl_add_u64 v[30:31], v[2:3], 0, s[12:13]
	v_readlane_b32 s49, v250, 27
	v_readlane_b32 s50, v250, 28
	v_readlane_b32 s51, v250, 29
	v_lshl_add_u64 v[30:31], v[30:31], 2, s[48:49]
	v_readlane_b32 s52, v250, 30
	v_readlane_b32 s53, v250, 31
	v_readlane_b32 s54, v250, 32
	v_readlane_b32 s55, v250, 33
	v_readlane_b32 s56, v250, 34
	v_readlane_b32 s57, v250, 35
	v_readlane_b32 s58, v250, 36
	v_readlane_b32 s59, v250, 37
	v_readlane_b32 s60, v250, 38
	v_readlane_b32 s61, v250, 39
	v_readlane_b32 s62, v250, 40
	v_readlane_b32 s63, v250, 41
	v_mul_f32_e32 v4, v4, v109
.LBB0_1529:
	ds_write_b32 v6, v4 offset:18720
	s_and_b64 vcc, exec, s[4:5]
	v_mul_f32_e32 v4, s30, v29
	s_cbranch_vccnz .LBB0_1531
	s_ashr_i32 s13, s12, 31
	v_ashrrev_i32_e32 v3, 31, v2
	v_readlane_b32 s48, v250, 26
	v_lshl_add_u64 v[30:31], v[2:3], 0, s[12:13]
	v_readlane_b32 s49, v250, 27
	v_readlane_b32 s50, v250, 28
	v_readlane_b32 s51, v250, 29
	v_lshl_add_u64 v[30:31], v[30:31], 2, s[48:49]
	v_readlane_b32 s52, v250, 30
	v_readlane_b32 s53, v250, 31
	v_readlane_b32 s54, v250, 32
	v_readlane_b32 s55, v250, 33
	v_readlane_b32 s56, v250, 34
	v_readlane_b32 s57, v250, 35
	v_readlane_b32 s58, v250, 36
	v_readlane_b32 s59, v250, 37
	v_readlane_b32 s60, v250, 38
	v_readlane_b32 s61, v250, 39
	v_readlane_b32 s62, v250, 40
	v_readlane_b32 s63, v250, 41
	v_mul_f32_e32 v4, v4, v110
.LBB0_1531:
	ds_write_b32 v6, v4 offset:20800
	s_and_b64 vcc, exec, s[4:5]
	v_mul_f32_e32 v4, s30, v28
	s_cbranch_vccnz .LBB0_1533
	s_ashr_i32 s13, s12, 31
	v_ashrrev_i32_e32 v3, 31, v2
	v_readlane_b32 s48, v250, 26
	v_lshl_add_u64 v[28:29], v[2:3], 0, s[12:13]
	v_readlane_b32 s49, v250, 27
	v_readlane_b32 s50, v250, 28
	v_readlane_b32 s51, v250, 29
	v_lshl_add_u64 v[28:29], v[28:29], 2, s[48:49]
	v_readlane_b32 s52, v250, 30
	v_readlane_b32 s53, v250, 31
	v_readlane_b32 s54, v250, 32
	v_readlane_b32 s55, v250, 33
	v_readlane_b32 s56, v250, 34
	v_readlane_b32 s57, v250, 35
	v_readlane_b32 s58, v250, 36
	v_readlane_b32 s59, v250, 37
	v_readlane_b32 s60, v250, 38
	v_readlane_b32 s61, v250, 39
	v_readlane_b32 s62, v250, 40
	v_readlane_b32 s63, v250, 41
	v_mul_f32_e32 v4, v4, v111
.LBB0_1533:
	ds_write_b32 v6, v4 offset:22880
	s_and_b64 vcc, exec, s[4:5]
	v_mul_f32_e32 v4, s30, v27
	s_cbranch_vccnz .LBB0_1535
	s_ashr_i32 s13, s12, 31
	v_ashrrev_i32_e32 v3, 31, v2
	v_readlane_b32 s48, v250, 26
	v_lshl_add_u64 v[28:29], v[2:3], 0, s[12:13]
	v_readlane_b32 s49, v250, 27
	v_readlane_b32 s50, v250, 28
	v_readlane_b32 s51, v250, 29
	v_lshl_add_u64 v[28:29], v[28:29], 2, s[48:49]
	v_readlane_b32 s52, v250, 30
	v_readlane_b32 s53, v250, 31
	v_readlane_b32 s54, v250, 32
	v_readlane_b32 s55, v250, 33
	v_readlane_b32 s56, v250, 34
	v_readlane_b32 s57, v250, 35
	v_readlane_b32 s58, v250, 36
	v_readlane_b32 s59, v250, 37
	v_readlane_b32 s60, v250, 38
	v_readlane_b32 s61, v250, 39
	v_readlane_b32 s62, v250, 40
	v_readlane_b32 s63, v250, 41
	v_mul_f32_e32 v4, v4, v112
.LBB0_1535:
	ds_write_b32 v6, v4 offset:24960
	s_and_b64 vcc, exec, s[4:5]
	v_mul_f32_e32 v4, s30, v26
	s_cbranch_vccnz .LBB0_1537
	s_ashr_i32 s13, s12, 31
	v_ashrrev_i32_e32 v3, 31, v2
	v_readlane_b32 s48, v250, 26
	v_lshl_add_u64 v[26:27], v[2:3], 0, s[12:13]
	v_readlane_b32 s49, v250, 27
	v_readlane_b32 s50, v250, 28
	v_readlane_b32 s51, v250, 29
	v_lshl_add_u64 v[26:27], v[26:27], 2, s[48:49]
	v_readlane_b32 s52, v250, 30
	v_readlane_b32 s53, v250, 31
	v_readlane_b32 s54, v250, 32
	v_readlane_b32 s55, v250, 33
	v_readlane_b32 s56, v250, 34
	v_readlane_b32 s57, v250, 35
	v_readlane_b32 s58, v250, 36
	v_readlane_b32 s59, v250, 37
	v_readlane_b32 s60, v250, 38
	v_readlane_b32 s61, v250, 39
	v_readlane_b32 s62, v250, 40
	v_readlane_b32 s63, v250, 41
	v_mul_f32_e32 v4, v4, v113
.LBB0_1537:
	ds_write_b32 v6, v4 offset:27040
	s_and_b64 vcc, exec, s[4:5]
	v_mul_f32_e32 v4, s30, v25
	s_cbranch_vccnz .LBB0_1539
	s_ashr_i32 s13, s12, 31
	v_ashrrev_i32_e32 v3, 31, v2
	v_readlane_b32 s48, v250, 26
	v_lshl_add_u64 v[26:27], v[2:3], 0, s[12:13]
	v_readlane_b32 s49, v250, 27
	v_readlane_b32 s50, v250, 28
	v_readlane_b32 s51, v250, 29
	v_lshl_add_u64 v[26:27], v[26:27], 2, s[48:49]
	v_readlane_b32 s52, v250, 30
	v_readlane_b32 s53, v250, 31
	v_readlane_b32 s54, v250, 32
	v_readlane_b32 s55, v250, 33
	v_readlane_b32 s56, v250, 34
	v_readlane_b32 s57, v250, 35
	v_readlane_b32 s58, v250, 36
	v_readlane_b32 s59, v250, 37
	v_readlane_b32 s60, v250, 38
	v_readlane_b32 s61, v250, 39
	v_readlane_b32 s62, v250, 40
	v_readlane_b32 s63, v250, 41
	v_mul_f32_e32 v4, v4, v114
.LBB0_1539:
	ds_write_b32 v6, v4 offset:29120
	s_and_b64 vcc, exec, s[4:5]
	v_mul_f32_e32 v4, s30, v23
	s_cbranch_vccnz .LBB0_1541
	s_ashr_i32 s13, s12, 31
	v_ashrrev_i32_e32 v3, 31, v2
	v_readlane_b32 s48, v250, 26
	v_lshl_add_u64 v[26:27], v[2:3], 0, s[12:13]
	v_readlane_b32 s49, v250, 27
	v_readlane_b32 s60, v250, 38
	v_readlane_b32 s61, v250, 39
	v_lshl_add_u64 v[26:27], v[26:27], 2, s[48:49]
	v_readlane_b32 s62, v250, 40
	v_readlane_b32 s63, v250, 41
	v_readlane_b32 s50, v250, 28
	v_readlane_b32 s51, v250, 29
	v_readlane_b32 s52, v250, 30
	v_readlane_b32 s53, v250, 31
	v_readlane_b32 s54, v250, 32
	v_readlane_b32 s55, v250, 33
	v_readlane_b32 s56, v250, 34
	v_readlane_b32 s57, v250, 35
	v_readlane_b32 s58, v250, 36
	v_readlane_b32 s59, v250, 37
	v_mul_f32_e32 v4, v4, v115

.LBB0_1544:
	s_and_b64 vcc, exec, s[4:5]
	v_mul_f32_e32 v3, s28, v24
	s_cbranch_vccnz .LBB0_1546
	v_add_u32_e32 v4, s2, v2
	v_readlane_b32 s48, v250, 26
	v_ashrrev_i32_e32 v5, 31, v4
	v_readlane_b32 s49, v250, 27
	v_readlane_b32 s50, v250, 28
	v_readlane_b32 s51, v250, 29
	v_lshl_add_u64 v[4:5], v[4:5], 2, s[48:49]
	global_load_dword v116, v[4:5], off
	global_load_dword v117, v[4:5], off offset:32
	global_load_dword v118, v[4:5], off offset:64
	global_load_dword v119, v[4:5], off offset:96
	global_load_dword v120, v[4:5], off offset:128
	global_load_dword v121, v[4:5], off offset:160
	global_load_dword v122, v[4:5], off offset:192
	global_load_dword v123, v[4:5], off offset:224
	v_readlane_b32 s52, v250, 30
	v_readlane_b32 s53, v250, 31
	v_readlane_b32 s54, v250, 32
	v_readlane_b32 s55, v250, 33
	v_readlane_b32 s56, v250, 34
	v_readlane_b32 s57, v250, 35
	v_readlane_b32 s58, v250, 36
	v_readlane_b32 s59, v250, 37
	v_readlane_b32 s60, v250, 38
	v_readlane_b32 s61, v250, 39
	v_readlane_b32 s62, v250, 40
	v_readlane_b32 s63, v250, 41
	s_waitcnt vmcnt(0)
	v_mul_f32_e32 v3, v3, v116
.LBB0_1546:
	s_and_b64 vcc, exec, s[4:5]
	v_mul_f32_e32 v4, s28, v22
	ds_write_b32 v6, v3 offset:33280
	s_cbranch_vccnz .LBB0_1548
	s_ashr_i32 s3, s2, 31
	v_ashrrev_i32_e32 v3, 31, v2
	v_readlane_b32 s48, v250, 26
	v_lshl_add_u64 v[22:23], v[2:3], 0, s[2:3]
	v_readlane_b32 s49, v250, 27
	v_readlane_b32 s50, v250, 28
	v_readlane_b32 s51, v250, 29
	v_lshl_add_u64 v[22:23], v[22:23], 2, s[48:49]
	v_readlane_b32 s52, v250, 30
	v_readlane_b32 s53, v250, 31
	v_readlane_b32 s54, v250, 32
	v_readlane_b32 s55, v250, 33
	v_readlane_b32 s56, v250, 34
	v_readlane_b32 s57, v250, 35
	v_readlane_b32 s58, v250, 36
	v_readlane_b32 s59, v250, 37
	v_readlane_b32 s60, v250, 38
	v_readlane_b32 s61, v250, 39
	v_readlane_b32 s62, v250, 40
	v_readlane_b32 s63, v250, 41
	v_mul_f32_e32 v4, v4, v117
.LBB0_1548:
	ds_write_b32 v6, v4 offset:35360
	s_and_b64 vcc, exec, s[4:5]
	v_mul_f32_e32 v4, s28, v21
	s_cbranch_vccnz .LBB0_1550
	s_ashr_i32 s3, s2, 31
	v_ashrrev_i32_e32 v3, 31, v2
	v_readlane_b32 s48, v250, 26
	v_lshl_add_u64 v[22:23], v[2:3], 0, s[2:3]
	v_readlane_b32 s49, v250, 27
	v_readlane_b32 s50, v250, 28
	v_readlane_b32 s51, v250, 29
	v_lshl_add_u64 v[22:23], v[22:23], 2, s[48:49]
	v_readlane_b32 s52, v250, 30
	v_readlane_b32 s53, v250, 31
	v_readlane_b32 s54, v250, 32
	v_readlane_b32 s55, v250, 33
	v_readlane_b32 s56, v250, 34
	v_readlane_b32 s57, v250, 35
	v_readlane_b32 s58, v250, 36
	v_readlane_b32 s59, v250, 37
	v_readlane_b32 s60, v250, 38
	v_readlane_b32 s61, v250, 39
	v_readlane_b32 s62, v250, 40
	v_readlane_b32 s63, v250, 41
	v_mul_f32_e32 v4, v4, v118
.LBB0_1550:
	ds_write_b32 v6, v4 offset:37440
	s_and_b64 vcc, exec, s[4:5]
	v_mul_f32_e32 v4, s28, v20
	s_cbranch_vccnz .LBB0_1552
	s_ashr_i32 s3, s2, 31
	v_ashrrev_i32_e32 v3, 31, v2
	v_readlane_b32 s48, v250, 26
	v_lshl_add_u64 v[20:21], v[2:3], 0, s[2:3]
	v_readlane_b32 s49, v250, 27
	v_readlane_b32 s50, v250, 28
	v_readlane_b32 s51, v250, 29
	v_lshl_add_u64 v[20:21], v[20:21], 2, s[48:49]
	v_readlane_b32 s52, v250, 30
	v_readlane_b32 s53, v250, 31
	v_readlane_b32 s54, v250, 32
	v_readlane_b32 s55, v250, 33
	v_readlane_b32 s56, v250, 34
	v_readlane_b32 s57, v250, 35
	v_readlane_b32 s58, v250, 36
	v_readlane_b32 s59, v250, 37
	v_readlane_b32 s60, v250, 38
	v_readlane_b32 s61, v250, 39
	v_readlane_b32 s62, v250, 40
	v_readlane_b32 s63, v250, 41
	v_mul_f32_e32 v4, v4, v119
.LBB0_1552:
	ds_write_b32 v6, v4 offset:39520
	s_and_b64 vcc, exec, s[4:5]
	v_mul_f32_e32 v4, s28, v19
	s_cbranch_vccnz .LBB0_1554
	s_ashr_i32 s3, s2, 31
	v_ashrrev_i32_e32 v3, 31, v2
	v_readlane_b32 s48, v250, 26
	v_lshl_add_u64 v[20:21], v[2:3], 0, s[2:3]
	v_readlane_b32 s49, v250, 27
	v_readlane_b32 s50, v250, 28
	v_readlane_b32 s51, v250, 29
	v_lshl_add_u64 v[20:21], v[20:21], 2, s[48:49]
	v_readlane_b32 s52, v250, 30
	v_readlane_b32 s53, v250, 31
	v_readlane_b32 s54, v250, 32
	v_readlane_b32 s55, v250, 33
	v_readlane_b32 s56, v250, 34
	v_readlane_b32 s57, v250, 35
	v_readlane_b32 s58, v250, 36
	v_readlane_b32 s59, v250, 37
	v_readlane_b32 s60, v250, 38
	v_readlane_b32 s61, v250, 39
	v_readlane_b32 s62, v250, 40
	v_readlane_b32 s63, v250, 41
	v_mul_f32_e32 v4, v4, v120
.LBB0_1554:
	ds_write_b32 v6, v4 offset:41600
	s_and_b64 vcc, exec, s[4:5]
	v_mul_f32_e32 v4, s28, v18
	s_cbranch_vccnz .LBB0_1556
	s_ashr_i32 s3, s2, 31
	v_ashrrev_i32_e32 v3, 31, v2
	v_readlane_b32 s48, v250, 26
	v_lshl_add_u64 v[18:19], v[2:3], 0, s[2:3]
	v_readlane_b32 s49, v250, 27
	v_readlane_b32 s50, v250, 28
	v_readlane_b32 s51, v250, 29
	v_lshl_add_u64 v[18:19], v[18:19], 2, s[48:49]
	v_readlane_b32 s52, v250, 30
	v_readlane_b32 s53, v250, 31
	v_readlane_b32 s54, v250, 32
	v_readlane_b32 s55, v250, 33
	v_readlane_b32 s56, v250, 34
	v_readlane_b32 s57, v250, 35
	v_readlane_b32 s58, v250, 36
	v_readlane_b32 s59, v250, 37
	v_readlane_b32 s60, v250, 38
	v_readlane_b32 s61, v250, 39
	v_readlane_b32 s62, v250, 40
	v_readlane_b32 s63, v250, 41
	v_mul_f32_e32 v4, v4, v121
.LBB0_1556:
	ds_write_b32 v6, v4 offset:43680
	s_and_b64 vcc, exec, s[4:5]
	v_mul_f32_e32 v4, s28, v17
	s_cbranch_vccnz .LBB0_1558
	s_ashr_i32 s3, s2, 31
	v_ashrrev_i32_e32 v3, 31, v2
	v_readlane_b32 s48, v250, 26
	v_lshl_add_u64 v[18:19], v[2:3], 0, s[2:3]
	v_readlane_b32 s49, v250, 27
	v_readlane_b32 s50, v250, 28
	v_readlane_b32 s51, v250, 29
	v_lshl_add_u64 v[18:19], v[18:19], 2, s[48:49]
	v_readlane_b32 s52, v250, 30
	v_readlane_b32 s53, v250, 31
	v_readlane_b32 s54, v250, 32
	v_readlane_b32 s55, v250, 33
	v_readlane_b32 s56, v250, 34
	v_readlane_b32 s57, v250, 35
	v_readlane_b32 s58, v250, 36
	v_readlane_b32 s59, v250, 37
	v_readlane_b32 s60, v250, 38
	v_readlane_b32 s61, v250, 39
	v_readlane_b32 s62, v250, 40
	v_readlane_b32 s63, v250, 41
	v_mul_f32_e32 v4, v4, v122
.LBB0_1558:
	ds_write_b32 v6, v4 offset:45760
	s_and_b64 vcc, exec, s[4:5]
	v_mul_f32_e32 v4, s28, v15
	s_cbranch_vccnz .LBB0_1560
	s_ashr_i32 s3, s2, 31
	v_ashrrev_i32_e32 v3, 31, v2
	v_readlane_b32 s48, v250, 26
	v_lshl_add_u64 v[18:19], v[2:3], 0, s[2:3]
	v_readlane_b32 s49, v250, 27
	v_readlane_b32 s60, v250, 38
	v_readlane_b32 s61, v250, 39
	v_lshl_add_u64 v[18:19], v[18:19], 2, s[48:49]
	v_readlane_b32 s62, v250, 40
	v_readlane_b32 s63, v250, 41
	v_readlane_b32 s50, v250, 28
	v_readlane_b32 s51, v250, 29
	v_readlane_b32 s52, v250, 30
	v_readlane_b32 s53, v250, 31
	v_readlane_b32 s54, v250, 32
	v_readlane_b32 s55, v250, 33
	v_readlane_b32 s56, v250, 34
	v_readlane_b32 s57, v250, 35
	v_readlane_b32 s58, v250, 36
	v_readlane_b32 s59, v250, 37
	v_mul_f32_e32 v4, v4, v123

.LBB0_1561:
	s_and_b64 vcc, exec, s[4:5]
	v_mul_f32_e32 v3, s25, v16
	s_cbranch_vccnz .LBB0_1563
	v_add_u32_e32 v4, s0, v2
	v_readlane_b32 s48, v250, 26
	v_ashrrev_i32_e32 v5, 31, v4
	v_readlane_b32 s49, v250, 27
	v_readlane_b32 s50, v250, 28
	v_readlane_b32 s51, v250, 29
	v_lshl_add_u64 v[4:5], v[4:5], 2, s[48:49]
	global_load_dword v124, v[4:5], off
	global_load_dword v125, v[4:5], off offset:32
	global_load_dword v126, v[4:5], off offset:64
	global_load_dword v127, v[4:5], off offset:96
	global_load_dword v128, v[4:5], off offset:128
	global_load_dword v129, v[4:5], off offset:160
	global_load_dword v130, v[4:5], off offset:192
	global_load_dword v131, v[4:5], off offset:224
	v_readlane_b32 s52, v250, 30
	v_readlane_b32 s53, v250, 31
	v_readlane_b32 s54, v250, 32
	v_readlane_b32 s55, v250, 33
	v_readlane_b32 s56, v250, 34
	v_readlane_b32 s57, v250, 35
	v_readlane_b32 s58, v250, 36
	v_readlane_b32 s59, v250, 37
	v_readlane_b32 s60, v250, 38
	v_readlane_b32 s61, v250, 39
	v_readlane_b32 s62, v250, 40
	v_readlane_b32 s63, v250, 41
	s_waitcnt vmcnt(0)
	v_mul_f32_e32 v3, v3, v124
.LBB0_1563:
	ds_write_b32 v6, v3 offset:49920
	v_mul_f32_e32 v4, s25, v14
	s_and_b64 vcc, exec, s[4:5]
	v_ashrrev_i32_e32 v3, 31, v2
	s_cbranch_vccnz .LBB0_1565
	s_ashr_i32 s1, s0, 31
	v_readlane_b32 s48, v250, 26
	v_lshl_add_u64 v[14:15], v[2:3], 0, s[0:1]
	v_readlane_b32 s49, v250, 27
	v_readlane_b32 s50, v250, 28
	v_readlane_b32 s51, v250, 29
	v_lshl_add_u64 v[14:15], v[14:15], 2, s[48:49]
	v_readlane_b32 s52, v250, 30
	v_readlane_b32 s53, v250, 31
	v_readlane_b32 s54, v250, 32
	v_readlane_b32 s55, v250, 33
	v_readlane_b32 s56, v250, 34
	v_readlane_b32 s57, v250, 35
	v_readlane_b32 s58, v250, 36
	v_readlane_b32 s59, v250, 37
	v_readlane_b32 s60, v250, 38
	v_readlane_b32 s61, v250, 39
	v_readlane_b32 s62, v250, 40
	v_readlane_b32 s63, v250, 41
	v_mul_f32_e32 v4, v4, v125
.LBB0_1565:
	ds_write_b32 v6, v4 offset:52000
	s_and_b64 vcc, exec, s[4:5]
	v_mul_f32_e32 v4, s25, v13
	s_cbranch_vccnz .LBB0_1567
	s_ashr_i32 s1, s0, 31
	v_readlane_b32 s48, v250, 26
	v_lshl_add_u64 v[14:15], v[2:3], 0, s[0:1]
	v_readlane_b32 s49, v250, 27
	v_readlane_b32 s50, v250, 28
	v_readlane_b32 s51, v250, 29
	v_lshl_add_u64 v[14:15], v[14:15], 2, s[48:49]
	v_readlane_b32 s52, v250, 30
	v_readlane_b32 s53, v250, 31
	v_readlane_b32 s54, v250, 32
	v_readlane_b32 s55, v250, 33
	v_readlane_b32 s56, v250, 34
	v_readlane_b32 s57, v250, 35
	v_readlane_b32 s58, v250, 36
	v_readlane_b32 s59, v250, 37
	v_readlane_b32 s60, v250, 38
	v_readlane_b32 s61, v250, 39
	v_readlane_b32 s62, v250, 40
	v_readlane_b32 s63, v250, 41
	v_mul_f32_e32 v4, v4, v126
.LBB0_1567:
	ds_write_b32 v6, v4 offset:54080
	s_and_b64 vcc, exec, s[4:5]
	v_mul_f32_e32 v4, s25, v12
	s_cbranch_vccnz .LBB0_1569
	s_ashr_i32 s1, s0, 31
	v_readlane_b32 s48, v250, 26
	v_lshl_add_u64 v[12:13], v[2:3], 0, s[0:1]
	v_readlane_b32 s49, v250, 27
	v_readlane_b32 s50, v250, 28
	v_readlane_b32 s51, v250, 29
	v_lshl_add_u64 v[12:13], v[12:13], 2, s[48:49]
	v_readlane_b32 s52, v250, 30
	v_readlane_b32 s53, v250, 31
	v_readlane_b32 s54, v250, 32
	v_readlane_b32 s55, v250, 33
	v_readlane_b32 s56, v250, 34
	v_readlane_b32 s57, v250, 35
	v_readlane_b32 s58, v250, 36
	v_readlane_b32 s59, v250, 37
	v_readlane_b32 s60, v250, 38
	v_readlane_b32 s61, v250, 39
	v_readlane_b32 s62, v250, 40
	v_readlane_b32 s63, v250, 41
	v_mul_f32_e32 v4, v4, v127
.LBB0_1569:
	ds_write_b32 v6, v4 offset:56160
	s_and_b64 vcc, exec, s[4:5]
	v_mul_f32_e32 v4, s25, v11
	s_cbranch_vccnz .LBB0_1571
	s_ashr_i32 s1, s0, 31
	v_readlane_b32 s48, v250, 26
	v_lshl_add_u64 v[12:13], v[2:3], 0, s[0:1]
	v_readlane_b32 s49, v250, 27
	v_readlane_b32 s50, v250, 28
	v_readlane_b32 s51, v250, 29
	v_lshl_add_u64 v[12:13], v[12:13], 2, s[48:49]
	v_readlane_b32 s52, v250, 30
	v_readlane_b32 s53, v250, 31
	v_readlane_b32 s54, v250, 32
	v_readlane_b32 s55, v250, 33
	v_readlane_b32 s56, v250, 34
	v_readlane_b32 s57, v250, 35
	v_readlane_b32 s58, v250, 36
	v_readlane_b32 s59, v250, 37
	v_readlane_b32 s60, v250, 38
	v_readlane_b32 s61, v250, 39
	v_readlane_b32 s62, v250, 40
	v_readlane_b32 s63, v250, 41
	v_mul_f32_e32 v4, v4, v128
.LBB0_1571:
	ds_write_b32 v6, v4 offset:58240
	s_and_b64 vcc, exec, s[4:5]
	v_mul_f32_e32 v4, s25, v10
	s_cbranch_vccnz .LBB0_1573
	s_ashr_i32 s1, s0, 31
	v_readlane_b32 s48, v250, 26
	v_lshl_add_u64 v[10:11], v[2:3], 0, s[0:1]
	v_readlane_b32 s49, v250, 27
	v_readlane_b32 s50, v250, 28
	v_readlane_b32 s51, v250, 29
	v_lshl_add_u64 v[10:11], v[10:11], 2, s[48:49]
	v_readlane_b32 s52, v250, 30
	v_readlane_b32 s53, v250, 31
	v_readlane_b32 s54, v250, 32
	v_readlane_b32 s55, v250, 33
	v_readlane_b32 s56, v250, 34
	v_readlane_b32 s57, v250, 35
	v_readlane_b32 s58, v250, 36
	v_readlane_b32 s59, v250, 37
	v_readlane_b32 s60, v250, 38
	v_readlane_b32 s61, v250, 39
	v_readlane_b32 s62, v250, 40
	v_readlane_b32 s63, v250, 41
	v_mul_f32_e32 v4, v4, v129
.LBB0_1573:
	ds_write_b32 v6, v4 offset:60320
	s_and_b64 vcc, exec, s[4:5]
	v_mul_f32_e32 v4, s25, v9
	s_cbranch_vccnz .LBB0_1575
	s_ashr_i32 s1, s0, 31
	v_readlane_b32 s48, v250, 26
	v_lshl_add_u64 v[10:11], v[2:3], 0, s[0:1]
	v_readlane_b32 s49, v250, 27
	v_readlane_b32 s50, v250, 28
	v_readlane_b32 s51, v250, 29
	v_lshl_add_u64 v[10:11], v[10:11], 2, s[48:49]
	v_readlane_b32 s52, v250, 30
	v_readlane_b32 s53, v250, 31
	v_readlane_b32 s54, v250, 32
	v_readlane_b32 s55, v250, 33
	v_readlane_b32 s56, v250, 34
	v_readlane_b32 s57, v250, 35
	v_readlane_b32 s58, v250, 36
	v_readlane_b32 s59, v250, 37
	v_readlane_b32 s60, v250, 38
	v_readlane_b32 s61, v250, 39
	v_readlane_b32 s62, v250, 40
	v_readlane_b32 s63, v250, 41
	v_mul_f32_e32 v4, v4, v130
.LBB0_1575:
	ds_write_b32 v6, v4 offset:62400
	s_and_b64 vcc, exec, s[4:5]
	v_mul_f32_e32 v4, s25, v8
	s_cbranch_vccnz .LBB0_1577
	s_ashr_i32 s1, s0, 31
	v_readlane_b32 s48, v250, 26
	v_lshl_add_u64 v[2:3], v[2:3], 0, s[0:1]
	v_readlane_b32 s49, v250, 27
	v_readlane_b32 s60, v250, 38
	v_readlane_b32 s61, v250, 39
	v_lshl_add_u64 v[2:3], v[2:3], 2, s[48:49]
	v_readlane_b32 s62, v250, 40
	v_readlane_b32 s63, v250, 41
	v_readlane_b32 s50, v250, 28
	v_readlane_b32 s51, v250, 29
	v_readlane_b32 s52, v250, 30
	v_readlane_b32 s53, v250, 31
	v_readlane_b32 s54, v250, 32
	v_readlane_b32 s55, v250, 33
	v_readlane_b32 s56, v250, 34
	v_readlane_b32 s57, v250, 35
	v_readlane_b32 s58, v250, 36
	v_readlane_b32 s59, v250, 37
	v_mul_f32_e32 v4, v4, v131
